# sc1_gemm
# baseline (speedup 1.0000x reference)
; __device__ __forceinline__ unsigned cvt_pk_bf16(float lo, float hi) { unsigned r; asm volatile("v_cvt_pk_bf16_f32 %0, %1, %2" : "=v"(r) : "v"(lo), "v"(hi)); return r; }
;     __device__ __forceinline__ void operator()(const f32x4 (&acc)[2][2][4][2], const Unit& u, int wr, int wc, int fr, int fq) const {
;         const int row0 = u.orow + wr * 64 + fr;
;         bf16_t* base; size_t rstride, bjstride;
;         if (u.ocol < 6144) { const int sect = u.ocol >> 11, hh0 = (u.ocol & 2047) >> 7, b = u.orow >= SEQ ? 1 : 0;
;             base = qkv + (size_t)sect * MTOK * 2048 + ((size_t)(b * 16 + hh0) * SEQ + (row0 & (SEQ - 1))) * 128 + wc * 32 + 8 * fq; rstride = 128; bjstride = (size_t)SEQ * 128; }
;         else { base = proj2 + (size_t)row0 * NP2 + (u.ocol - 6144) + wc * 32 + 8 * fq; rstride = NP2; bjstride = HALF; }
; #pragma unroll
;         for (int ai = 0; ai < 2; ++ai)
; #pragma unroll
;             for (int m = 0; m < 4; ++m) { bf16_t* rowp = base + (size_t)(ai * HALF + m * 16) * rstride;
; #pragma unroll
;                 for (int bj = 0; bj < 2; ++bj) { const f32x4 v0 = acc[ai][bj][m][0], v1 = acc[ai][bj][m][1];
;                     u32x4 w; w.x = cvt_pk_bf16(v0[0], v0[1]); w.y = cvt_pk_bf16(v0[2], v0[3]); w.z = cvt_pk_bf16(v1[0], v1[1]); w.w = cvt_pk_bf16(v1[2], v1[3]);
;                     __builtin_nontemporal_store(w, (u32x4*)(rowp + bj * bjstride)); } }
.LBB0_182:
	v_lshl_add_u64 v[150:151], v[150:151], 0, s[8:9]
	v_lshl_add_u64 v[150:151], v[150:151], 0, v[142:143]
	s_lshl_b32 s26, s26, 1
	s_mov_b32 s27, s9
	v_cvt_pk_bf16_f32 v124, v124, v125
	v_cvt_pk_bf16_f32 v125, v126, v127
	v_cvt_pk_bf16_f32 v126, v120, v121
	v_cvt_pk_bf16_f32 v127, v122, v123
	global_store_dwordx4 v[150:151], v[124:127], off sc1
	v_cvt_pk_bf16_f32 v116, v116, v117
	v_cvt_pk_bf16_f32 v117, v118, v119
	v_cvt_pk_bf16_f32 v118, v108, v109
	v_lshl_add_u64 v[108:109], v[150:151], 0, s[26:27]
	s_lshl_b32 s28, s36, 5
	s_mov_b32 s29, s9
	v_cvt_pk_bf16_f32 v119, v110, v111
	global_store_dwordx4 v[108:109], v[116:119], off sc1
	v_cvt_pk_bf16_f32 v108, v112, v113
	v_cvt_pk_bf16_f32 v109, v114, v115
	v_cvt_pk_bf16_f32 v110, v104, v105
	v_cvt_pk_bf16_f32 v111, v106, v107
	s_mulk_i32 s36, 0xa0
	s_nop 0
	v_lshl_add_u64 v[116:117], v[150:151], 0, s[28:29]
	global_store_dwordx4 v[116:117], v[108:111], off sc1
	v_cvt_pk_bf16_f32 v96, v96, v97
	v_cvt_pk_bf16_f32 v97, v98, v99
	v_cvt_pk_bf16_f32 v98, v88, v89
	v_lshl_add_u64 v[88:89], v[116:117], 0, s[26:27]
	v_cvt_pk_bf16_f32 v99, v90, v91
	global_store_dwordx4 v[88:89], v[96:99], off sc1
	v_cvt_pk_bf16_f32 v88, v100, v101
	v_cvt_pk_bf16_f32 v89, v102, v103
	v_cvt_pk_bf16_f32 v90, v92, v93
	v_cvt_pk_bf16_f32 v91, v94, v95
	s_mov_b32 s37, s9
	s_nop 0
	v_lshl_add_u64 v[96:97], v[116:117], 0, s[28:29]
	global_store_dwordx4 v[96:97], v[88:91], off sc1
	v_cvt_pk_bf16_f32 v80, v80, v81
	v_cvt_pk_bf16_f32 v81, v82, v83
	v_cvt_pk_bf16_f32 v82, v72, v73
	v_lshl_add_u64 v[72:73], v[96:97], 0, s[26:27]
	v_cvt_pk_bf16_f32 v83, v74, v75
	global_store_dwordx4 v[72:73], v[80:83], off sc1
	v_cvt_pk_bf16_f32 v72, v84, v85
	v_cvt_pk_bf16_f32 v73, v86, v87
	v_cvt_pk_bf16_f32 v74, v76, v77
	v_cvt_pk_bf16_f32 v75, v78, v79
	s_and_b64 vcc, exec, s[0:1]
	s_nop 0
	v_lshl_add_u64 v[80:81], v[96:97], 0, s[28:29]
	global_store_dwordx4 v[80:81], v[72:75], off sc1
	v_cvt_pk_bf16_f32 v68, v68, v69
	v_cvt_pk_bf16_f32 v69, v70, v71
	v_cvt_pk_bf16_f32 v70, v64, v65
	v_lshl_add_u64 v[64:65], v[80:81], 0, s[26:27]
	v_cvt_pk_bf16_f32 v71, v66, v67
	global_store_dwordx4 v[64:65], v[68:71], off sc1
	v_lshl_add_u64 v[64:65], v[80:81], 0, s[36:37]
	v_cvt_pk_bf16_f32 v60, v60, v61
	v_cvt_pk_bf16_f32 v61, v62, v63
	v_cvt_pk_bf16_f32 v62, v56, v57
	v_cvt_pk_bf16_f32 v63, v58, v59
	global_store_dwordx4 v[64:65], v[60:63], off sc1
	v_cvt_pk_bf16_f32 v48, v48, v49
	v_cvt_pk_bf16_f32 v49, v50, v51
	v_cvt_pk_bf16_f32 v50, v40, v41
	v_lshl_add_u64 v[40:41], v[64:65], 0, s[26:27]
	v_cvt_pk_bf16_f32 v51, v42, v43
	global_store_dwordx4 v[40:41], v[48:51], off sc1
	v_cvt_pk_bf16_f32 v40, v52, v53
	v_cvt_pk_bf16_f32 v41, v54, v55
	v_cvt_pk_bf16_f32 v42, v44, v45
	v_cvt_pk_bf16_f32 v43, v46, v47
	s_mov_b32 s66, s65
	s_nop 0
	v_lshl_add_u64 v[48:49], v[64:65], 0, s[28:29]
	global_store_dwordx4 v[48:49], v[40:43], off sc1
	v_cvt_pk_bf16_f32 v32, v32, v33
	v_cvt_pk_bf16_f32 v33, v34, v35
	v_cvt_pk_bf16_f32 v34, v24, v25
	v_lshl_add_u64 v[24:25], v[48:49], 0, s[26:27]
	v_cvt_pk_bf16_f32 v35, v26, v27
	global_store_dwordx4 v[24:25], v[32:35], off sc1
	v_cvt_pk_bf16_f32 v24, v36, v37
	v_cvt_pk_bf16_f32 v25, v38, v39
	v_cvt_pk_bf16_f32 v26, v28, v29
	v_cvt_pk_bf16_f32 v27, v30, v31
	s_mov_b64 s[36:37], s[24:25]
	s_nop 0
	v_lshl_add_u64 v[32:33], v[48:49], 0, s[28:29]
	global_store_dwordx4 v[32:33], v[24:27], off sc1
	v_cvt_pk_bf16_f32 v16, v16, v17
	v_cvt_pk_bf16_f32 v17, v18, v19
	v_cvt_pk_bf16_f32 v18, v8, v9
	v_lshl_add_u64 v[8:9], v[32:33], 0, s[26:27]
	v_cvt_pk_bf16_f32 v19, v10, v11
	global_store_dwordx4 v[8:9], v[16:19], off sc1
	v_cvt_pk_bf16_f32 v8, v20, v21
	v_cvt_pk_bf16_f32 v9, v22, v23
	v_cvt_pk_bf16_f32 v10, v12, v13
	v_cvt_pk_bf16_f32 v11, v14, v15
	s_nop 1
	v_lshl_add_u64 v[16:17], v[32:33], 0, s[28:29]
	global_store_dwordx4 v[16:17], v[8:11], off sc1
	v_cvt_pk_bf16_f32 v4, v4, v5
	v_cvt_pk_bf16_f32 v5, v6, v7
	v_cvt_pk_bf16_f32 v6, v0, v1
	v_lshl_add_u64 v[0:1], v[16:17], 0, s[26:27]
	s_mov_b32 s26, s64
	s_mov_b64 s[28:29], s[22:23]
	v_cvt_pk_bf16_f32 v7, v2, v3
	global_store_dwordx4 v[0:1], v[4:7], off sc1
	s_cbranch_vccnz .LBB0_191

; #define PG8_STAGE(bufoff, gbase, voff) do { _Pragma("unroll") for (int _i = 0; _i < 2; ++_i) \
;         __builtin_amdgcn_global_load_lds((const unsigned*)((const char*)(gbase) + (voff)[_i]), (LAS unsigned*)(lds + (bufoff) + ldsw + _i * 8192), 16, 0, 0); } while (0)
; #define PG8_LDA(dst, b, h) do { _Pragma("unroll") for (int m = 0; m < 4; ++m) _Pragma("unroll") for (int k = 0; k < 2; ++k) dst[m][k] = *(const LAS bf16x8*)(lds + PG8_SA(b, h) + aoff + m * 2048 + k * 1024); } while (0)
; #define PG8_LDB(dst, b, h) do { _Pragma("unroll") for (int n = 0; n < 2; ++n) _Pragma("unroll") for (int k = 0; k < 2; ++k) dst[n][k] = *(const LAS bf16x8*)(lds + PG8_SB(b, h) + boff + n * 2048 + k * 1024); } while (0)
; #define PG8_MMA(ai, bj, At, Bt) do { __builtin_amdgcn_s_setprio(1); _Pragma("unroll") for (int m = 0; m < 4; ++m) _Pragma("unroll") for (int n = 0; n < 2; ++n) _Pragma("unroll") for (int k = 0; k < 2; ++k) \
;         acc[ai][bj][m][n] = __builtin_amdgcn_mfma_f32_16x16x32_bf16(Bt[n][k], At[m][k], acc[ai][bj][m][n], 0, 0, 0); __builtin_amdgcn_s_setprio(0); } while (0)
; #define PG8_WAIT_V(n) asm volatile("s_waitcnt vmcnt(" #n ")" ::: "memory")
; #define PG8_WAIT_L(n) asm volatile("s_waitcnt lgkmcnt(" #n ")" ::: "memory")
; #define PG8_BAR __builtin_amdgcn_s_barrier()
; #define PG8_SCHED __builtin_amdgcn_sched_barrier(0)
; template <class Epi, class Job>
; __device__ __forceinline__ void gemm_phase(LAS unsigned char* lds, const Job& S, const Epi& E) {
;     ...
;             PG8_LDB(B0, 0, 0); PG8_SCHED; PG8_LDA(At, 0, 0); PG8_STAGE(PG8_SA(1, 1), a1 + hstepA, voffA);
;             PG8_WAIT_L(8); PG8_BAR; PG8_WAIT_L(0); PG8_MMA(0, 0, At, B0); PG8_BAR; PG8_SCHED;
;             PG8_LDB(B1, 0, 1); PG8_STAGE(PG8_SB(0, 0), b2, voffB);
;             PG8_BAR; PG8_WAIT_L(0); PG8_MMA(0, 1, At, B1); PG8_BAR;
;             PG8_LDA(At, 0, 1); PG8_STAGE(PG8_SA(0, 0), a2, voffA);
;             PG8_BAR; PG8_WAIT_L(0); PG8_MMA(1, 0, At, B0); PG8_BAR; PG8_SCHED;
;             PG8_STAGE(PG8_SB(0, 1), b2 + hstepB, voffB);
;             PG8_WAIT_V(6); PG8_BAR; PG8_MMA(1, 1, At, B1); PG8_BAR;
.LBB0_457:
	s_add_i32 m0, s57, 0xc000
	s_nop 0
	global_load_lds_dwordx4 v132, s[36:37]
	s_add_i32 m0, s57, 0xe000
	s_nop 0
	global_load_lds_dwordx4 v142, s[36:37]
	s_add_u32 s46, s36, 0xfff00080
	s_addc_u32 s47, s37, -1
	s_cmp_eq_u32 s81, 60
	s_cselect_b32 s49, s29, s47
	s_cselect_b32 s48, s28, s46
	s_cselect_b32 s47, s31, s80
	s_cselect_b32 s46, s30, s79
	ds_read_b128 v[174:177], v151 offset:1024
	ds_read_b128 v[182:185], v151 offset:3072
	ds_read_b128 v[190:193], v151 offset:5120
	ds_read_b128 v[198:201], v151 offset:7168
	s_waitcnt lgkmcnt(8)
	s_waitcnt lgkmcnt(0)
	s_setprio 1
	s_barrier
	v_mfma_f32_16x16x32_bf16 v[124:127], v[154:157], v[170:173], v[124:127]
	ds_read_b128 v[202:205], v152
	v_mfma_f32_16x16x32_bf16 v[120:123], v[162:165], v[170:173], v[120:123]
	v_mfma_f32_16x16x32_bf16 v[116:119], v[154:157], v[178:181], v[116:119]
	ds_read_b128 v[206:209], v152 offset:1024
	v_mfma_f32_16x16x32_bf16 v[108:111], v[162:165], v[178:181], v[108:111]
	v_mfma_f32_16x16x32_bf16 v[100:103], v[154:157], v[186:189], v[100:103]
	ds_read_b128 v[210:213], v152 offset:2048
	v_mfma_f32_16x16x32_bf16 v[92:95], v[162:165], v[186:189], v[92:95]
	v_mfma_f32_16x16x32_bf16 v[84:87], v[154:157], v[194:197], v[84:87]
	ds_read_b128 v[214:217], v152 offset:3072
	v_mfma_f32_16x16x32_bf16 v[76:79], v[162:165], v[194:197], v[76:79]
	v_mfma_f32_16x16x32_bf16 v[124:127], v[158:161], v[174:177], v[124:127]
	v_mfma_f32_16x16x32_bf16 v[120:123], v[166:169], v[174:177], v[120:123]
	v_mfma_f32_16x16x32_bf16 v[116:119], v[158:161], v[182:185], v[116:119]
	v_mfma_f32_16x16x32_bf16 v[108:111], v[166:169], v[182:185], v[108:111]
	v_mfma_f32_16x16x32_bf16 v[100:103], v[158:161], v[190:193], v[100:103]
	v_mfma_f32_16x16x32_bf16 v[92:95], v[166:169], v[190:193], v[92:95]
	v_mfma_f32_16x16x32_bf16 v[84:87], v[158:161], v[198:201], v[84:87]
	v_mfma_f32_16x16x32_bf16 v[76:79], v[166:169], v[198:201], v[76:79]
	s_barrier
	s_setprio 0
	s_add_i32 s82, s66, s56
	s_mov_b32 m0, s82
	s_nop 0
	global_load_lds_dwordx4 v136, s[46:47]
	s_add_i32 m0, s82, 0x2000
	s_nop 0
	global_load_lds_dwordx4 v140, s[46:47]
	s_waitcnt lgkmcnt(0)
	s_setprio 1
	s_barrier
	v_mfma_f32_16x16x32_bf16 v[112:115], v[202:205], v[170:173], v[112:115]
	v_mfma_f32_16x16x32_bf16 v[104:107], v[210:213], v[170:173], v[104:107]
	v_mfma_f32_16x16x32_bf16 v[96:99], v[202:205], v[178:181], v[96:99]
	v_mfma_f32_16x16x32_bf16 v[88:91], v[210:213], v[178:181], v[88:91]
	v_mfma_f32_16x16x32_bf16 v[80:83], v[202:205], v[186:189], v[80:83]
	v_mfma_f32_16x16x32_bf16 v[72:75], v[210:213], v[186:189], v[72:75]
	v_mfma_f32_16x16x32_bf16 v[68:71], v[202:205], v[194:197], v[68:71]
	v_mfma_f32_16x16x32_bf16 v[64:67], v[210:213], v[194:197], v[64:67]
	v_mfma_f32_16x16x32_bf16 v[112:115], v[206:209], v[174:177], v[112:115]
	ds_read_b128 v[170:173], v151 offset:16384
	v_mfma_f32_16x16x32_bf16 v[104:107], v[214:217], v[174:177], v[104:107]
	v_mfma_f32_16x16x32_bf16 v[96:99], v[206:209], v[182:185], v[96:99]
	ds_read_b128 v[178:181], v151 offset:18432
	v_mfma_f32_16x16x32_bf16 v[88:91], v[214:217], v[182:185], v[88:91]
	v_mfma_f32_16x16x32_bf16 v[80:83], v[206:209], v[190:193], v[80:83]
	ds_read_b128 v[186:189], v151 offset:20480
	v_mfma_f32_16x16x32_bf16 v[72:75], v[214:217], v[190:193], v[72:75]
	v_mfma_f32_16x16x32_bf16 v[68:71], v[206:209], v[198:201], v[68:71]
	ds_read_b128 v[194:197], v151 offset:22528
	v_mfma_f32_16x16x32_bf16 v[64:67], v[214:217], v[198:201], v[64:67]
	s_barrier
	s_setprio 0
	s_mov_b32 m0, s57
	s_mov_b64 s[100:101], s[48:49]
	global_load_lds_dwordx4 v134, s[48:49]
	s_mov_b32 m0, s58
	s_nop 0
	global_load_lds_dwordx4 v138, s[48:49]
	ds_read_b128 v[174:177], v151 offset:17408
	ds_read_b128 v[182:185], v151 offset:19456
	ds_read_b128 v[190:193], v151 offset:21504
	ds_read_b128 v[198:201], v151 offset:23552
	s_waitcnt vmcnt(8)
	s_waitcnt lgkmcnt(0)
	s_setprio 1
	s_barrier
	v_mfma_f32_16x16x32_bf16 v[60:63], v[154:157], v[170:173], v[60:63]
	v_mfma_f32_16x16x32_bf16 v[56:59], v[162:165], v[170:173], v[56:59]
	v_mfma_f32_16x16x32_bf16 v[52:55], v[154:157], v[178:181], v[52:55]
	v_mfma_f32_16x16x32_bf16 v[44:47], v[162:165], v[178:181], v[44:47]
	v_mfma_f32_16x16x32_bf16 v[36:39], v[154:157], v[186:189], v[36:39]
	v_mfma_f32_16x16x32_bf16 v[28:31], v[162:165], v[186:189], v[28:31]
	v_mfma_f32_16x16x32_bf16 v[20:23], v[154:157], v[194:197], v[20:23]
	v_mfma_f32_16x16x32_bf16 v[12:15], v[162:165], v[194:197], v[12:15]
	v_mfma_f32_16x16x32_bf16 v[60:63], v[158:161], v[174:177], v[60:63]
	v_mfma_f32_16x16x32_bf16 v[56:59], v[166:169], v[174:177], v[56:59]
	v_mfma_f32_16x16x32_bf16 v[52:55], v[158:161], v[182:185], v[52:55]
	v_mfma_f32_16x16x32_bf16 v[44:47], v[166:169], v[182:185], v[44:47]
	v_mfma_f32_16x16x32_bf16 v[36:39], v[158:161], v[190:193], v[36:39]
	v_mfma_f32_16x16x32_bf16 v[28:31], v[166:169], v[190:193], v[28:31]
	v_mfma_f32_16x16x32_bf16 v[20:23], v[158:161], v[198:201], v[20:23]
	v_mfma_f32_16x16x32_bf16 v[12:15], v[166:169], v[198:201], v[12:15]
	s_barrier
	s_setprio 0
	s_add_u32 s82, s46, 0x100000
	s_addc_u32 s83, s47, 0
	s_add_i32 s84, s67, s56
	s_mov_b32 m0, s84
	s_nop 0
	global_load_lds_dwordx4 v136, s[82:83]
	s_add_i32 m0, s84, 0x2000
	s_nop 0
	global_load_lds_dwordx4 v140, s[82:83]
	s_waitcnt vmcnt(6)
	s_setprio 1
	v_add_u32_e32 v153, 0x18000, v148
	s_barrier
; #define PG8_STAGE(bufoff, gbase, voff) do { _Pragma("unroll") for (int _i = 0; _i < 2; ++_i) \
;         __builtin_amdgcn_global_load_lds((const unsigned*)((const char*)(gbase) + (voff)[_i]), (LAS unsigned*)(lds + (bufoff) + ldsw + _i * 8192), 16, 0, 0); } while (0)
; #define PG8_LDA(dst, b, h) do { _Pragma("unroll") for (int m = 0; m < 4; ++m) _Pragma("unroll") for (int k = 0; k < 2; ++k) dst[m][k] = *(const LAS bf16x8*)(lds + PG8_SA(b, h) + aoff + m * 2048 + k * 1024); } while (0)
; #define PG8_LDB(dst, b, h) do { _Pragma("unroll") for (int n = 0; n < 2; ++n) _Pragma("unroll") for (int k = 0; k < 2; ++k) dst[n][k] = *(const LAS bf16x8*)(lds + PG8_SB(b, h) + boff + n * 2048 + k * 1024); } while (0)
; #define PG8_MMA(ai, bj, At, Bt) do { __builtin_amdgcn_s_setprio(1); _Pragma("unroll") for (int m = 0; m < 4; ++m) _Pragma("unroll") for (int n = 0; n < 2; ++n) _Pragma("unroll") for (int k = 0; k < 2; ++k) \
;         acc[ai][bj][m][n] = __builtin_amdgcn_mfma_f32_16x16x32_bf16(Bt[n][k], At[m][k], acc[ai][bj][m][n], 0, 0, 0); __builtin_amdgcn_s_setprio(0); } while (0)
; #define PG8_WAIT_V(n) asm volatile("s_waitcnt vmcnt(" #n ")" ::: "memory")
; #define PG8_WAIT_L(n) asm volatile("s_waitcnt lgkmcnt(" #n ")" ::: "memory")
; #define PG8_BAR __builtin_amdgcn_s_barrier()
; #define PG8_SCHED __builtin_amdgcn_sched_barrier(0)
; template <class Epi, class Job>
; __device__ __forceinline__ void gemm_phase(LAS unsigned char* lds, const Job& S, const Epi& E) {
;     ...
;             PG8_WAIT_V(6); PG8_BAR; PG8_MMA(1, 1, At, B1); PG8_BAR;
;             PG8_LDB(B0, 1, 0); PG8_SCHED; PG8_LDA(At, 1, 0); PG8_STAGE(PG8_SA(0, 1), a2 + hstepA, voffA);
;             PG8_WAIT_L(8); PG8_BAR; PG8_WAIT_L(0); PG8_MMA(0, 0, At, B0); PG8_BAR; PG8_SCHED;
;             PG8_LDB(B1, 1, 1); PG8_STAGE(PG8_SB(1, 0), b3, voffB);
;             PG8_BAR; PG8_WAIT_L(0); PG8_MMA(0, 1, At, B1); PG8_BAR;
;             PG8_LDA(At, 1, 1); PG8_STAGE(PG8_SA(1, 0), a3, voffA);
	v_mfma_f32_16x16x32_bf16 v[48:51], v[202:205], v[170:173], v[48:51]
	ds_read_b128 v[154:157], v153
	v_mfma_f32_16x16x32_bf16 v[40:43], v[210:213], v[170:173], v[40:43]
	v_mfma_f32_16x16x32_bf16 v[32:35], v[202:205], v[178:181], v[32:35]
	ds_read_b128 v[158:161], v153 offset:1024
	v_mfma_f32_16x16x32_bf16 v[24:27], v[210:213], v[178:181], v[24:27]
	v_mfma_f32_16x16x32_bf16 v[16:19], v[202:205], v[186:189], v[16:19]
	ds_read_b128 v[162:165], v153 offset:2048
	v_mfma_f32_16x16x32_bf16 v[8:11], v[210:213], v[186:189], v[8:11]
	v_mfma_f32_16x16x32_bf16 v[4:7], v[202:205], v[194:197], v[4:7]
	ds_read_b128 v[166:169], v153 offset:3072
	v_mfma_f32_16x16x32_bf16 v[0:3], v[210:213], v[194:197], v[0:3]
	v_mfma_f32_16x16x32_bf16 v[48:51], v[206:209], v[174:177], v[48:51]
	ds_read_b128 v[170:173], v151 offset:32768
	v_mfma_f32_16x16x32_bf16 v[40:43], v[214:217], v[174:177], v[40:43]
	v_mfma_f32_16x16x32_bf16 v[32:35], v[206:209], v[182:185], v[32:35]
	ds_read_b128 v[178:181], v151 offset:34816
	v_mfma_f32_16x16x32_bf16 v[24:27], v[214:217], v[182:185], v[24:27]
	v_mfma_f32_16x16x32_bf16 v[16:19], v[206:209], v[190:193], v[16:19]
	ds_read_b128 v[186:189], v151 offset:36864
	v_mfma_f32_16x16x32_bf16 v[8:11], v[214:217], v[190:193], v[8:11]
	v_mfma_f32_16x16x32_bf16 v[4:7], v[206:209], v[198:201], v[4:7]
	ds_read_b128 v[194:197], v151 offset:38912
	v_mfma_f32_16x16x32_bf16 v[0:3], v[214:217], v[198:201], v[0:3]
	s_barrier
	s_setprio 0
	s_add_i32 s82, 0, 0x18000
	v_add_u32_e32 v153, s82, v148
	s_add_u32 s48, s48, 0x100000
	s_addc_u32 s49, s49, 0
	s_mov_b32 m0, s59
	s_nop 0
	global_load_lds_dwordx4 v134, s[48:49]
	s_mov_b32 m0, s60
	s_nop 0
	global_load_lds_dwordx4 v138, s[48:49]
	ds_read_b128 v[174:177], v151 offset:33792
	ds_read_b128 v[182:185], v151 offset:35840
	ds_read_b128 v[190:193], v151 offset:37888
	ds_read_b128 v[198:201], v151 offset:39936
	s_waitcnt lgkmcnt(8)
	s_waitcnt lgkmcnt(0)
	s_setprio 1
	v_add_u32_e32 v153, 0x1c000, v148
	s_barrier
	v_mfma_f32_16x16x32_bf16 v[124:127], v[154:157], v[170:173], v[124:127]
	ds_read_b128 v[202:205], v153
	v_mfma_f32_16x16x32_bf16 v[120:123], v[162:165], v[170:173], v[120:123]
	v_mfma_f32_16x16x32_bf16 v[116:119], v[154:157], v[178:181], v[116:119]
	ds_read_b128 v[206:209], v153 offset:1024
	v_mfma_f32_16x16x32_bf16 v[108:111], v[162:165], v[178:181], v[108:111]
	v_mfma_f32_16x16x32_bf16 v[100:103], v[154:157], v[186:189], v[100:103]
	ds_read_b128 v[210:213], v153 offset:2048
	v_mfma_f32_16x16x32_bf16 v[92:95], v[162:165], v[186:189], v[92:95]
	v_mfma_f32_16x16x32_bf16 v[84:87], v[154:157], v[194:197], v[84:87]
	ds_read_b128 v[214:217], v153 offset:3072
	v_mfma_f32_16x16x32_bf16 v[76:79], v[162:165], v[194:197], v[76:79]
	v_mfma_f32_16x16x32_bf16 v[124:127], v[158:161], v[174:177], v[124:127]
	v_mfma_f32_16x16x32_bf16 v[120:123], v[166:169], v[174:177], v[120:123]
	v_mfma_f32_16x16x32_bf16 v[116:119], v[158:161], v[182:185], v[116:119]
	v_mfma_f32_16x16x32_bf16 v[108:111], v[166:169], v[182:185], v[108:111]
	v_mfma_f32_16x16x32_bf16 v[100:103], v[158:161], v[190:193], v[100:103]
	v_mfma_f32_16x16x32_bf16 v[92:95], v[166:169], v[190:193], v[92:95]
	v_mfma_f32_16x16x32_bf16 v[84:87], v[158:161], v[198:201], v[84:87]
	v_mfma_f32_16x16x32_bf16 v[76:79], v[166:169], v[198:201], v[76:79]
	s_barrier
	s_setprio 0
	s_add_i32 s48, 0, 0x1c000
	s_add_i32 s49, s82, s56
	v_add_u32_e32 v153, s48, v148
	s_add_u32 s98, s46, s8
	s_addc_u32 s99, s47, s9
	s_mov_b32 m0, s49
	s_nop 0
	global_load_lds_dwordx4 v136, s[98:99]
	s_add_i32 m0, s49, 0x2000
	s_nop 0
	global_load_lds_dwordx4 v140, s[98:99]
	s_waitcnt lgkmcnt(0)
	s_setprio 1
	s_barrier
	v_mfma_f32_16x16x32_bf16 v[112:115], v[202:205], v[170:173], v[112:115]
	v_mfma_f32_16x16x32_bf16 v[104:107], v[210:213], v[170:173], v[104:107]
	v_mfma_f32_16x16x32_bf16 v[96:99], v[202:205], v[178:181], v[96:99]
	v_mfma_f32_16x16x32_bf16 v[88:91], v[210:213], v[178:181], v[88:91]
	v_mfma_f32_16x16x32_bf16 v[80:83], v[202:205], v[186:189], v[80:83]
	v_mfma_f32_16x16x32_bf16 v[72:75], v[210:213], v[186:189], v[72:75]
	v_mfma_f32_16x16x32_bf16 v[68:71], v[202:205], v[194:197], v[68:71]
	v_mfma_f32_16x16x32_bf16 v[64:67], v[210:213], v[194:197], v[64:67]
	v_mfma_f32_16x16x32_bf16 v[112:115], v[206:209], v[174:177], v[112:115]
	ds_read_b128 v[170:173], v151 offset:49152
	v_mfma_f32_16x16x32_bf16 v[104:107], v[214:217], v[174:177], v[104:107]
	v_mfma_f32_16x16x32_bf16 v[96:99], v[206:209], v[182:185], v[96:99]
	ds_read_b128 v[178:181], v151 offset:51200
	v_mfma_f32_16x16x32_bf16 v[88:91], v[214:217], v[182:185], v[88:91]
	v_mfma_f32_16x16x32_bf16 v[80:83], v[206:209], v[190:193], v[80:83]
	ds_read_b128 v[186:189], v151 offset:53248
	v_mfma_f32_16x16x32_bf16 v[72:75], v[214:217], v[190:193], v[72:75]
	v_mfma_f32_16x16x32_bf16 v[68:71], v[206:209], v[198:201], v[68:71]
	ds_read_b128 v[194:197], v151 offset:55296
	v_mfma_f32_16x16x32_bf16 v[64:67], v[214:217], v[198:201], v[64:67]
	s_barrier
	s_setprio 0
	s_mov_b32 m0, s62
	s_add_u32 s100, s100, s8
	s_addc_u32 s101, s101, s9
	global_load_lds_dwordx4 v134, s[100:101]
	s_mov_b32 m0, s63
	s_nop 0
	global_load_lds_dwordx4 v138, s[100:101]
	ds_read_b128 v[174:177], v151 offset:50176
	ds_read_b128 v[182:185], v151 offset:52224
	ds_read_b128 v[190:193], v151 offset:54272
	ds_read_b128 v[198:201], v151 offset:56320
	s_waitcnt vmcnt(8)
	s_waitcnt lgkmcnt(0)
	s_setprio 1
	s_barrier
; #define PG8_STAGE(bufoff, gbase, voff) do { _Pragma("unroll") for (int _i = 0; _i < 2; ++_i) \
;         __builtin_amdgcn_global_load_lds((const unsigned*)((const char*)(gbase) + (voff)[_i]), (LAS unsigned*)(lds + (bufoff) + ldsw + _i * 8192), 16, 0, 0); } while (0)
; #define PG8_MMA(ai, bj, At, Bt) do { __builtin_amdgcn_s_setprio(1); _Pragma("unroll") for (int m = 0; m < 4; ++m) _Pragma("unroll") for (int n = 0; n < 2; ++n) _Pragma("unroll") for (int k = 0; k < 2; ++k) \
;         acc[ai][bj][m][n] = __builtin_amdgcn_mfma_f32_16x16x32_bf16(Bt[n][k], At[m][k], acc[ai][bj][m][n], 0, 0, 0); __builtin_amdgcn_s_setprio(0); } while (0)
; #define PG8_WAIT_V(n) asm volatile("s_waitcnt vmcnt(" #n ")" ::: "memory")
; #define PG8_WAIT_L(n) asm volatile("s_waitcnt lgkmcnt(" #n ")" ::: "memory")
; #define PG8_BAR __builtin_amdgcn_s_barrier()
; #define PG8_SCHED __builtin_amdgcn_sched_barrier(0)
; template <class Epi, class Job>
; __device__ __forceinline__ void gemm_phase(LAS unsigned char* lds, const Job& S, const Epi& E) {
;     ...
;             PG8_BAR; PG8_WAIT_L(0); PG8_MMA(1, 0, At, B0); PG8_BAR; PG8_SCHED;
;             PG8_STAGE(PG8_SB(1, 1), b3 + hstepB, voffB);
;             PG8_WAIT_V(6); PG8_BAR; PG8_MMA(1, 1, At, B1); PG8_BAR;
;         }
	v_mfma_f32_16x16x32_bf16 v[60:63], v[154:157], v[170:173], v[60:63]
	v_mfma_f32_16x16x32_bf16 v[56:59], v[162:165], v[170:173], v[56:59]
	v_mfma_f32_16x16x32_bf16 v[52:55], v[154:157], v[178:181], v[52:55]
	v_mfma_f32_16x16x32_bf16 v[44:47], v[162:165], v[178:181], v[44:47]
	v_mfma_f32_16x16x32_bf16 v[36:39], v[154:157], v[186:189], v[36:39]
	v_mfma_f32_16x16x32_bf16 v[28:31], v[162:165], v[186:189], v[28:31]
	v_mfma_f32_16x16x32_bf16 v[20:23], v[154:157], v[194:197], v[20:23]
	v_mfma_f32_16x16x32_bf16 v[12:15], v[162:165], v[194:197], v[12:15]
	v_mfma_f32_16x16x32_bf16 v[60:63], v[158:161], v[174:177], v[60:63]
	v_mfma_f32_16x16x32_bf16 v[56:59], v[166:169], v[174:177], v[56:59]
	v_mfma_f32_16x16x32_bf16 v[52:55], v[158:161], v[182:185], v[52:55]
	v_mfma_f32_16x16x32_bf16 v[44:47], v[166:169], v[182:185], v[44:47]
	v_mfma_f32_16x16x32_bf16 v[36:39], v[158:161], v[190:193], v[36:39]
	v_mfma_f32_16x16x32_bf16 v[28:31], v[166:169], v[190:193], v[28:31]
	v_mfma_f32_16x16x32_bf16 v[20:23], v[158:161], v[198:201], v[20:23]
	v_mfma_f32_16x16x32_bf16 v[12:15], v[166:169], v[198:201], v[12:15]
	s_barrier
	s_setprio 0
	s_add_u32 s46, s46, 0x100080
	s_addc_u32 s47, s47, 0
	s_add_i32 s48, s48, s56
	s_mov_b32 m0, s48
	s_nop 0
	global_load_lds_dwordx4 v136, s[46:47]
	s_add_i32 m0, s48, 0x2000
	s_nop 0
	global_load_lds_dwordx4 v140, s[46:47]
	s_waitcnt vmcnt(6)
	s_setprio 1
	s_barrier
	v_mfma_f32_16x16x32_bf16 v[48:51], v[202:205], v[170:173], v[48:51]
	ds_read_b128 v[154:157], v150
	v_mfma_f32_16x16x32_bf16 v[40:43], v[210:213], v[170:173], v[40:43]
	v_mfma_f32_16x16x32_bf16 v[32:35], v[202:205], v[178:181], v[32:35]
	ds_read_b128 v[158:161], v150 offset:1024
	v_mfma_f32_16x16x32_bf16 v[24:27], v[210:213], v[178:181], v[24:27]
	v_mfma_f32_16x16x32_bf16 v[16:19], v[202:205], v[186:189], v[16:19]
	ds_read_b128 v[162:165], v150 offset:2048
	v_mfma_f32_16x16x32_bf16 v[8:11], v[210:213], v[186:189], v[8:11]
	v_mfma_f32_16x16x32_bf16 v[4:7], v[202:205], v[194:197], v[4:7]
	ds_read_b128 v[166:169], v150 offset:3072
	v_mfma_f32_16x16x32_bf16 v[0:3], v[210:213], v[194:197], v[0:3]
	v_mfma_f32_16x16x32_bf16 v[48:51], v[206:209], v[174:177], v[48:51]
	ds_read_b128 v[170:173], v151
	v_mfma_f32_16x16x32_bf16 v[40:43], v[214:217], v[174:177], v[40:43]
	v_mfma_f32_16x16x32_bf16 v[32:35], v[206:209], v[182:185], v[32:35]
	ds_read_b128 v[178:181], v151 offset:2048
	v_mfma_f32_16x16x32_bf16 v[24:27], v[214:217], v[182:185], v[24:27]
	v_mfma_f32_16x16x32_bf16 v[16:19], v[206:209], v[190:193], v[16:19]
	ds_read_b128 v[186:189], v151 offset:4096
	v_mfma_f32_16x16x32_bf16 v[8:11], v[214:217], v[190:193], v[8:11]
	v_mfma_f32_16x16x32_bf16 v[4:7], v[206:209], v[198:201], v[4:7]
	ds_read_b128 v[194:197], v151 offset:6144
	v_mfma_f32_16x16x32_bf16 v[0:3], v[214:217], v[198:201], v[0:3]
	s_barrier
	s_setprio 0
	s_add_i32 s81, s81, 2
	s_add_u32 s36, s36, 0x100
	s_addc_u32 s37, s37, 0
	s_add_u32 s79, s79, 0x100
	s_addc_u32 s80, s80, 0
	s_cmp_gt_u32 s81, 61
	s_cbranch_scc0 .LBB0_457
; __device__ __forceinline__ unsigned cvt_pk_bf16(float lo, float hi) { unsigned r; asm volatile("v_cvt_pk_bf16_f32 %0, %1, %2" : "=v"(r) : "v"(lo), "v"(hi)); return r; }
;     __device__ __forceinline__ void operator()(const f32x4 (&acc)[2][2][4][2], const Unit& u, int wr, int wc, int fr, int fq) const {
;         const int row0 = u.orow + wr * 64 + fr, col0 = u.ocol + wc * 32 + 8 * fq;
; #pragma unroll
;         for (int ai = 0; ai < 2; ++ai)
; #pragma unroll
;             for (int m = 0; m < 4; ++m) { bf16_t* rowp = O + (size_t)(row0 + ai * HALF + m * 16) * ldc + col0;
; #pragma unroll
;                 for (int bj = 0; bj < 2; ++bj) { const f32x4 v0 = acc[ai][bj][m][0], v1 = acc[ai][bj][m][1];
;                     u32x4 w; w.x = cvt_pk_bf16(v0[0], v0[1]); w.y = cvt_pk_bf16(v0[2], v0[3]); w.z = cvt_pk_bf16(v1[0], v1[1]); w.w = cvt_pk_bf16(v1[2], v1[3]);
;                     if (nt) __builtin_nontemporal_store(w, (u32x4*)(rowp + bj * HALF)); else *(u32x4*)(rowp + bj * HALF) = w; } }
	s_waitcnt lgkmcnt(0)
	v_add_u32_e32 v146, s78, v131
	v_ashrrev_i32_e32 v147, 31, v146
	v_add_u32_e32 v154, s77, v149
	v_lshlrev_b64 v[146:147], 13, v[146:147]
	v_ashrrev_i32_e32 v155, 31, v154
	v_lshl_add_u64 v[146:147], s[18:19], 0, v[146:147]
	v_lshl_add_u64 v[146:147], v[154:155], 1, v[146:147]
	v_cvt_pk_bf16_f32 v124, v124, v125
	v_cvt_pk_bf16_f32 v125, v126, v127
	v_cvt_pk_bf16_f32 v126, v120, v121
	v_cvt_pk_bf16_f32 v127, v122, v123
	global_store_dwordx4 v[146:147], v[124:127], off sc1
	v_cvt_pk_bf16_f32 v112, v112, v113
	v_cvt_pk_bf16_f32 v113, v114, v115
	v_cvt_pk_bf16_f32 v114, v104, v105
	v_cvt_pk_bf16_f32 v115, v106, v107
	global_store_dwordx4 v[146:147], v[112:115], off offset:256 sc1
	v_cvt_pk_bf16_f32 v104, v116, v117
	v_cvt_pk_bf16_f32 v105, v118, v119
	v_cvt_pk_bf16_f32 v106, v108, v109
	v_add_co_u32_e32 v108, vcc, s68, v146
	s_nop 0
	v_lshl_add_u64 v[112:113], v[146:147], 0, s[10:11]
	v_addc_co_u32_e32 v109, vcc, 0, v147, vcc
	v_cvt_pk_bf16_f32 v107, v110, v111
	global_store_dwordx4 v[108:109], v[104:107], off sc1
	v_cvt_pk_bf16_f32 v96, v96, v97
	v_cvt_pk_bf16_f32 v97, v98, v99
	v_cvt_pk_bf16_f32 v98, v88, v89
	v_cvt_pk_bf16_f32 v99, v90, v91
	global_store_dwordx4 v[112:113], v[96:99], off offset:256 sc1
	v_cvt_pk_bf16_f32 v88, v100, v101
	v_cvt_pk_bf16_f32 v89, v102, v103
	v_cvt_pk_bf16_f32 v90, v92, v93
	v_add_co_u32_e32 v92, vcc, s69, v146
	s_nop 0
	v_lshl_add_u64 v[96:97], v[146:147], 0, s[12:13]
	v_addc_co_u32_e32 v93, vcc, 0, v147, vcc
	v_cvt_pk_bf16_f32 v91, v94, v95
	global_store_dwordx4 v[92:93], v[88:91], off sc1
	v_cvt_pk_bf16_f32 v80, v80, v81
	v_cvt_pk_bf16_f32 v81, v82, v83
	v_cvt_pk_bf16_f32 v82, v72, v73
	v_cvt_pk_bf16_f32 v83, v74, v75
	global_store_dwordx4 v[96:97], v[80:83], off offset:256 sc1
	v_cvt_pk_bf16_f32 v72, v84, v85
	v_cvt_pk_bf16_f32 v73, v86, v87
	v_cvt_pk_bf16_f32 v74, v76, v77
	v_add_co_u32_e32 v76, vcc, s70, v146
	s_nop 0
	v_lshl_add_u64 v[80:81], v[146:147], 0, s[20:21]
	v_addc_co_u32_e32 v77, vcc, 0, v147, vcc
	v_cvt_pk_bf16_f32 v75, v78, v79
	global_store_dwordx4 v[76:77], v[72:75], off sc1
	v_cvt_pk_bf16_f32 v68, v68, v69
	v_cvt_pk_bf16_f32 v69, v70, v71
	v_cvt_pk_bf16_f32 v70, v64, v65
	v_cvt_pk_bf16_f32 v71, v66, v67
	global_store_dwordx4 v[80:81], v[68:71], off offset:256 sc1
	v_cvt_pk_bf16_f32 v60, v60, v61
	v_cvt_pk_bf16_f32 v61, v62, v63
	v_cvt_pk_bf16_f32 v62, v56, v57
	v_add_co_u32_e32 v56, vcc, s71, v146
	v_lshl_add_u64 v[64:65], v[146:147], 0, s[6:7]
	s_nop 0
	v_addc_co_u32_e32 v57, vcc, 0, v147, vcc
	v_cvt_pk_bf16_f32 v63, v58, v59
	global_store_dwordx4 v[56:57], v[60:63], off sc1
	v_cvt_pk_bf16_f32 v48, v48, v49
	v_cvt_pk_bf16_f32 v49, v50, v51
	v_cvt_pk_bf16_f32 v50, v40, v41
	v_cvt_pk_bf16_f32 v51, v42, v43
	global_store_dwordx4 v[64:65], v[48:51], off offset:256 sc1
	v_cvt_pk_bf16_f32 v40, v52, v53
	v_cvt_pk_bf16_f32 v41, v54, v55
	v_cvt_pk_bf16_f32 v42, v44, v45
	v_add_co_u32_e32 v44, vcc, s72, v146
	s_nop 0
	v_lshl_add_u64 v[48:49], v[146:147], 0, s[22:23]
	v_addc_co_u32_e32 v45, vcc, 0, v147, vcc
	v_cvt_pk_bf16_f32 v43, v46, v47
	global_store_dwordx4 v[44:45], v[40:43], off sc1
	v_cvt_pk_bf16_f32 v32, v32, v33
	v_cvt_pk_bf16_f32 v33, v34, v35
	v_cvt_pk_bf16_f32 v34, v24, v25
	v_cvt_pk_bf16_f32 v35, v26, v27
	global_store_dwordx4 v[48:49], v[32:35], off offset:256 sc1
	v_cvt_pk_bf16_f32 v24, v36, v37
	v_cvt_pk_bf16_f32 v25, v38, v39
	v_cvt_pk_bf16_f32 v26, v28, v29
	v_add_co_u32_e32 v28, vcc, s73, v146
	s_nop 0
	v_lshl_add_u64 v[32:33], v[146:147], 0, s[24:25]
	v_addc_co_u32_e32 v29, vcc, 0, v147, vcc
	v_cvt_pk_bf16_f32 v27, v30, v31
	global_store_dwordx4 v[28:29], v[24:27], off sc1
	v_cvt_pk_bf16_f32 v16, v16, v17
	v_cvt_pk_bf16_f32 v17, v18, v19
	v_cvt_pk_bf16_f32 v18, v8, v9
	v_cvt_pk_bf16_f32 v19, v10, v11
	global_store_dwordx4 v[32:33], v[16:19], off offset:256 sc1
	v_cvt_pk_bf16_f32 v8, v20, v21
	v_cvt_pk_bf16_f32 v9, v22, v23
	v_cvt_pk_bf16_f32 v10, v12, v13
	v_add_co_u32_e32 v12, vcc, s74, v146
	s_nop 0
	v_lshl_add_u64 v[16:17], v[146:147], 0, s[26:27]
	v_addc_co_u32_e32 v13, vcc, 0, v147, vcc
	s_and_b64 vcc, exec, s[4:5]
	s_mov_b32 s77, s76
	s_mov_b32 s78, s75
	s_mov_b64 s[46:47], s[30:31]
	s_mov_b64 s[36:37], s[28:29]
	v_cvt_pk_bf16_f32 v11, v14, v15
	global_store_dwordx4 v[12:13], v[8:11], off sc1
	v_cvt_pk_bf16_f32 v4, v4, v5
	v_cvt_pk_bf16_f32 v5, v6, v7
	v_cvt_pk_bf16_f32 v6, v0, v1
	v_cvt_pk_bf16_f32 v7, v2, v3
	global_store_dwordx4 v[16:17], v[4:7], off offset:256 sc1
	s_cbranch_vccz .LBB0_450
	s_waitcnt vmcnt(0)
	s_cmpk_gt_u32 s50, 0xff
	s_cbranch_scc1 .LBB0_461
	s_barrier
